# every block leader issues an L2 write-back when it arrives at a grid barrier, so the flush overlaps the wait for stragglers
# baseline (speedup 1.0000x reference)
; __device__ __forceinline__ void xcd_barrier(const XcdBarrier& b) {
;     asm volatile("s_waitcnt vmcnt(0)" ::: "memory");
;     __syncthreads();
;     int t0_ = threadIdx.x; asm volatile("" : "+v"(t0_));
;     if (t0_ == 0) {
;         unsigned* bar = b.bar;
;         __builtin_amdgcn_s_waitcnt(0);
;         unsigned nloc = b.st[0], nx = b.st[1];
;         if (nloc == 0u) { xcd_barrier_complete(bar, b.x, nloc, nx); b.st[0] = nloc; b.st[1] = nx; }
.LBB0_109:
	s_mov_b64 s[36:37], s[72:73]
	s_getreg_b32 s0, hwreg(HW_REG_XCC_ID, 0, 4)
	s_waitcnt vmcnt(0)
	v_mov_b32_e32 v0, v154
	s_waitcnt lgkmcnt(0)
	s_barrier
	s_nop 0
	v_cmp_eq_u32_e32 vcc, 0, v0
	s_and_saveexec_b64 s[34:35], vcc
	s_cbranch_execz .LBB0_153
	s_add_i32 s1, 0, 0x21000
	v_mov_b32_e32 v0, s1
	s_waitcnt vmcnt(0) expcnt(0) lgkmcnt(0)
	buffer_wbl2 sc1
	ds_read_b32 v2, v0
	s_add_i32 s1, 0, 0x21004
	v_mov_b32_e32 v0, s1
	ds_read_b32 v0, v0
	s_and_b32 s15, s0, 15
	s_waitcnt lgkmcnt(1)
	v_cmp_ne_u32_e32 vcc, 0, v2
	s_cbranch_vccnz .LBB0_124
	s_add_u32 s0, s36, 0x100200
	s_addc_u32 s1, s37, 0
	s_add_u32 s4, s36, 0x100400
	s_addc_u32 s5, s37, 0
	s_add_u32 s6, s36, 0x100500
	s_addc_u32 s7, s37, 0
	s_add_u32 s8, s36, 0x100600
	s_addc_u32 s9, s37, 0
	s_add_u32 s10, s36, 0x100700
	s_addc_u32 s11, s37, 0
	s_add_u32 s12, s36, 0x100800
	s_addc_u32 s13, s37, 0
	s_add_u32 s16, s36, 0x100900
	s_addc_u32 s17, s37, 0
	s_add_u32 s18, s36, 0x100a00
	s_addc_u32 s19, s37, 0
	s_add_u32 s20, s36, 0x100b00
	s_addc_u32 s21, s37, 0
	s_add_u32 s24, s36, 0x100c00
	s_addc_u32 s25, s37, 0
	s_add_u32 s26, s36, 0x100d00
	s_addc_u32 s27, s37, 0
	s_add_u32 s28, s36, 0x100e00
	s_addc_u32 s29, s37, 0
	s_add_u32 s30, s36, 0x100f00
	s_addc_u32 s31, s37, 0
	s_add_u32 s38, s36, 0x101000
	s_addc_u32 s39, s37, 0
	s_add_u32 s42, s36, 0x101100
	s_addc_u32 s43, s37, 0
	s_add_u32 s44, s36, 0x101200
	s_addc_u32 s45, s37, 0
	s_add_u32 s46, s36, 0x101300
	s_mul_i32 s22, s75, s81
	s_addc_u32 s47, s37, 0
	s_mul_i32 s22, s22, s74
	s_mov_b32 s23, 1
	s_mov_b64 s[2:3], 0
	s_waitcnt lgkmcnt(0)
	v_mov_b64_e32 v[0:1], s[4:5]
	v_mov_b64_e32 v[2:3], s[6:7]
	v_mov_b64_e32 v[4:5], s[8:9]
	v_mov_b64_e32 v[6:7], s[10:11]
	v_mov_b64_e32 v[8:9], s[12:13]
	v_mov_b64_e32 v[10:11], s[16:17]
	v_mov_b64_e32 v[12:13], s[18:19]
	v_mov_b64_e32 v[14:15], s[20:21]
	v_mov_b64_e32 v[16:17], s[24:25]
	v_mov_b64_e32 v[18:19], s[26:27]
	v_mov_b64_e32 v[20:21], s[28:29]
	v_mov_b64_e32 v[22:23], s[30:31]
	v_mov_b64_e32 v[24:25], s[38:39]
	v_mov_b64_e32 v[26:27], s[42:43]
	v_mov_b64_e32 v[28:29], s[44:45]
	v_mov_b64_e32 v[30:31], s[46:47]
	s_branch .LBB0_114

; __device__ __forceinline__ void xcd_barrier(const XcdBarrier& b) {
;     asm volatile("s_waitcnt vmcnt(0)" ::: "memory");
;     __syncthreads();
;     int t0_ = threadIdx.x; asm volatile("" : "+v"(t0_));
;     if (t0_ == 0) {
;         unsigned* bar = b.bar;
;         __builtin_amdgcn_s_waitcnt(0);
;         unsigned nloc = b.st[0], nx = b.st[1];
;         if (nloc == 0u) { xcd_barrier_complete(bar, b.x, nloc, nx); b.st[0] = nloc; b.st[1] = nx; }
.LBB0_169:
	s_mov_b64 s[36:37], s[72:73]
	s_getreg_b32 s0, hwreg(HW_REG_XCC_ID, 0, 4)
	s_waitcnt vmcnt(0)
	v_mov_b32_e32 v0, v154
	s_barrier
	s_nop 0
	v_cmp_eq_u32_e32 vcc, 0, v0
	s_and_saveexec_b64 s[34:35], vcc
	s_cbranch_execz .LBB0_213
	s_add_i32 s1, 0, 0x21000
	v_mov_b32_e32 v0, s1
	s_waitcnt vmcnt(0) expcnt(0) lgkmcnt(0)
	buffer_wbl2 sc1
	ds_read_b32 v2, v0
	s_add_i32 s1, 0, 0x21004
	v_mov_b32_e32 v0, s1
	ds_read_b32 v0, v0
	s_and_b32 s15, s0, 15
	s_waitcnt lgkmcnt(1)
	v_cmp_ne_u32_e32 vcc, 0, v2
	s_cbranch_vccnz .LBB0_184
	s_add_u32 s0, s36, 0x100200
	s_addc_u32 s1, s37, 0
	s_add_u32 s4, s36, 0x100400
	s_addc_u32 s5, s37, 0
	s_add_u32 s6, s36, 0x100500
	s_addc_u32 s7, s37, 0
	s_add_u32 s8, s36, 0x100600
	s_addc_u32 s9, s37, 0
	s_add_u32 s10, s36, 0x100700
	s_addc_u32 s11, s37, 0
	s_add_u32 s12, s36, 0x100800
	s_addc_u32 s13, s37, 0
	s_add_u32 s16, s36, 0x100900
	s_addc_u32 s17, s37, 0
	s_add_u32 s18, s36, 0x100a00
	s_addc_u32 s19, s37, 0
	s_add_u32 s20, s36, 0x100b00
	s_addc_u32 s21, s37, 0
	s_add_u32 s24, s36, 0x100c00
	s_addc_u32 s25, s37, 0
	s_add_u32 s26, s36, 0x100d00
	s_addc_u32 s27, s37, 0
	s_add_u32 s28, s36, 0x100e00
	s_addc_u32 s29, s37, 0
	s_add_u32 s30, s36, 0x100f00
	s_addc_u32 s31, s37, 0
	s_add_u32 s44, s36, 0x101000
	s_addc_u32 s45, s37, 0
	s_add_u32 s46, s36, 0x101100
	s_addc_u32 s47, s37, 0
	s_add_u32 s48, s36, 0x101200
	s_addc_u32 s49, s37, 0
	s_add_u32 s50, s36, 0x101300
	s_mul_i32 s22, s75, s81
	s_addc_u32 s51, s37, 0
	s_mul_i32 s22, s22, s74
	s_mov_b32 s23, 1
	s_mov_b64 s[2:3], 0
	s_waitcnt lgkmcnt(0)
	v_mov_b64_e32 v[0:1], s[4:5]
	v_mov_b64_e32 v[2:3], s[6:7]
	v_mov_b64_e32 v[4:5], s[8:9]
	v_mov_b64_e32 v[6:7], s[10:11]
	v_mov_b64_e32 v[8:9], s[12:13]
	v_mov_b64_e32 v[10:11], s[16:17]
	v_mov_b64_e32 v[12:13], s[18:19]
	v_mov_b64_e32 v[14:15], s[20:21]
	v_mov_b64_e32 v[16:17], s[24:25]
	v_mov_b64_e32 v[18:19], s[26:27]
	v_mov_b64_e32 v[20:21], s[28:29]
	v_mov_b64_e32 v[22:23], s[30:31]
	v_mov_b64_e32 v[24:25], s[44:45]
	v_mov_b64_e32 v[26:27], s[46:47]
	v_mov_b64_e32 v[28:29], s[48:49]
	v_mov_b64_e32 v[30:31], s[50:51]
	s_branch .LBB0_174

; __device__ __forceinline__ unsigned xb_ld(unsigned* p)              { return __hip_atomic_load(p, __ATOMIC_RELAXED, __HIP_MEMORY_SCOPE_AGENT); }
; __device__ __forceinline__ unsigned xb_add(unsigned* p, unsigned v) { return __hip_atomic_fetch_add(p, v, __ATOMIC_RELAXED, __HIP_MEMORY_SCOPE_AGENT); }
; __device__ __forceinline__ void xcd_barrier_complete(unsigned* bar, unsigned x, unsigned& nloc, unsigned& nx) {
;     const unsigned G = gridDim.x * gridDim.y * gridDim.z;
;     unsigned sum, cnt, mine, sp = 0u;
;     for (;;) {
;         sum = 0u; cnt = 0u; mine = 0u;
; #pragma unroll
;         for (unsigned j = 0; j < 16; ++j) { const unsigned c = xb_ld(&bar[XB_XCNT(j)]); sum += c; cnt += (c > 0u) ? 1u : 0u; mine = (j == x) ? c : mine; }
; __device__ __forceinline__ void xcd_barrier(const XcdBarrier& b) {
;     asm volatile("s_waitcnt vmcnt(0)" ::: "memory");
;     __syncthreads();
;     int t0_ = threadIdx.x; asm volatile("" : "+v"(t0_));
;     if (t0_ == 0) {
;         unsigned* bar = b.bar;
;         __builtin_amdgcn_s_waitcnt(0);
;         unsigned nloc = b.st[0], nx = b.st[1];
;         if (nloc == 0u) { xcd_barrier_complete(bar, b.x, nloc, nx); b.st[0] = nloc; b.st[1] = nx; }
;         const unsigned old = xb_add(&bar[XB_XSUB(b.x)], 1u);
.LBB0_251:
	s_mov_b64 s[44:45], s[72:73]
	s_getreg_b32 s2, hwreg(HW_REG_XCC_ID, 0, 4)
	s_waitcnt vmcnt(0)
	v_mov_b32_e32 v0, v154
	s_waitcnt lgkmcnt(0)
	s_barrier
	s_nop 0
	v_cmp_eq_u32_e32 vcc, 0, v0
	s_and_saveexec_b64 s[36:37], vcc
	s_cbranch_execz .LBB0_295
	s_add_i32 s3, 0, 0x21000
	v_mov_b32_e32 v0, s3
	s_waitcnt vmcnt(0) expcnt(0) lgkmcnt(0)
	buffer_wbl2 sc1
	ds_read_b32 v2, v0
	s_add_i32 s3, 0, 0x21004
	v_mov_b32_e32 v0, s3
	ds_read_b32 v0, v0
	s_and_b32 s15, s2, 15
	s_waitcnt lgkmcnt(1)
	v_cmp_ne_u32_e32 vcc, 0, v2
	s_cbranch_vccnz .LBB0_266
	s_add_u32 s2, s44, 0x100200
	s_addc_u32 s3, s45, 0
	s_add_u32 s6, s44, 0x100400
	s_addc_u32 s7, s45, 0
	s_add_u32 s8, s44, 0x100500
	s_addc_u32 s9, s45, 0
	s_add_u32 s10, s44, 0x100600
	s_addc_u32 s11, s45, 0
	s_add_u32 s12, s44, 0x100700
	s_addc_u32 s13, s45, 0
	s_add_u32 s16, s44, 0x100800
	s_addc_u32 s17, s45, 0
	s_add_u32 s18, s44, 0x100900
	s_addc_u32 s19, s45, 0
	s_add_u32 s20, s44, 0x100a00
	s_addc_u32 s21, s45, 0
	s_add_u32 s22, s44, 0x100b00
	s_addc_u32 s23, s45, 0
	s_add_u32 s26, s44, 0x100c00
	s_addc_u32 s27, s45, 0
	s_add_u32 s28, s44, 0x100d00
	s_addc_u32 s29, s45, 0
	s_add_u32 s30, s44, 0x100e00
	s_addc_u32 s31, s45, 0
	s_add_u32 s34, s44, 0x100f00
	s_addc_u32 s35, s45, 0
	s_add_u32 s46, s44, 0x101000
	s_addc_u32 s47, s45, 0
	s_add_u32 s48, s44, 0x101100
	s_addc_u32 s49, s45, 0
	s_add_u32 s50, s44, 0x101200
	s_addc_u32 s51, s45, 0
	s_add_u32 s52, s44, 0x101300
	s_mul_i32 s24, s75, s81
	s_addc_u32 s53, s45, 0
	s_mul_i32 s24, s24, s74
	s_mov_b32 s25, 1
	s_mov_b64 s[4:5], 0
	s_waitcnt lgkmcnt(0)
	v_mov_b64_e32 v[0:1], s[6:7]
	v_mov_b64_e32 v[2:3], s[8:9]
	v_mov_b64_e32 v[4:5], s[10:11]
	v_mov_b64_e32 v[6:7], s[12:13]
	v_mov_b64_e32 v[8:9], s[16:17]
	v_mov_b64_e32 v[10:11], s[18:19]
	v_mov_b64_e32 v[12:13], s[20:21]
	v_mov_b64_e32 v[14:15], s[22:23]
	v_mov_b64_e32 v[16:17], s[26:27]
	v_mov_b64_e32 v[18:19], s[28:29]
	v_mov_b64_e32 v[20:21], s[30:31]
	v_mov_b64_e32 v[22:23], s[34:35]
	v_mov_b64_e32 v[24:25], s[46:47]
	v_mov_b64_e32 v[26:27], s[48:49]
	v_mov_b64_e32 v[28:29], s[50:51]
	v_mov_b64_e32 v[30:31], s[52:53]
	s_branch .LBB0_256

; __device__ __forceinline__ unsigned xb_ld(unsigned* p)              { return __hip_atomic_load(p, __ATOMIC_RELAXED, __HIP_MEMORY_SCOPE_AGENT); }
; __device__ __forceinline__ unsigned xb_add(unsigned* p, unsigned v) { return __hip_atomic_fetch_add(p, v, __ATOMIC_RELAXED, __HIP_MEMORY_SCOPE_AGENT); }
; __device__ __forceinline__ void xcd_barrier_complete(unsigned* bar, unsigned x, unsigned& nloc, unsigned& nx) {
;     const unsigned G = gridDim.x * gridDim.y * gridDim.z;
;     unsigned sum, cnt, mine, sp = 0u;
;     for (;;) {
;         sum = 0u; cnt = 0u; mine = 0u;
; #pragma unroll
;         for (unsigned j = 0; j < 16; ++j) { const unsigned c = xb_ld(&bar[XB_XCNT(j)]); sum += c; cnt += (c > 0u) ? 1u : 0u; mine = (j == x) ? c : mine; }
; __device__ __forceinline__ void xcd_barrier(const XcdBarrier& b) {
;     asm volatile("s_waitcnt vmcnt(0)" ::: "memory");
;     __syncthreads();
;     int t0_ = threadIdx.x; asm volatile("" : "+v"(t0_));
;     if (t0_ == 0) {
;         unsigned* bar = b.bar;
;         __builtin_amdgcn_s_waitcnt(0);
;         unsigned nloc = b.st[0], nx = b.st[1];
;         if (nloc == 0u) { xcd_barrier_complete(bar, b.x, nloc, nx); b.st[0] = nloc; b.st[1] = nx; }
;         const unsigned old = xb_add(&bar[XB_XSUB(b.x)], 1u);
.LBB0_403:
	s_mov_b64 s[46:47], s[72:73]
	s_getreg_b32 s2, hwreg(HW_REG_XCC_ID, 0, 4)
	s_waitcnt vmcnt(0)
	v_mov_b32_e32 v0, v154
	s_barrier
	s_nop 0
	v_cmp_eq_u32_e32 vcc, 0, v0
	s_and_saveexec_b64 s[44:45], vcc
	s_cbranch_execz .LBB0_447
	s_add_i32 s3, 0, 0x21000
	v_mov_b32_e32 v0, s3
	s_waitcnt vmcnt(0) expcnt(0) lgkmcnt(0)
	buffer_wbl2 sc1
	ds_read_b32 v2, v0
	s_add_i32 s3, 0, 0x21004
	v_mov_b32_e32 v0, s3
	ds_read_b32 v0, v0
	s_and_b32 s15, s2, 15
	s_waitcnt lgkmcnt(1)
	v_cmp_ne_u32_e32 vcc, 0, v2
	s_cbranch_vccnz .LBB0_418
	s_add_u32 s2, s46, 0x100200
	s_addc_u32 s3, s47, 0
	s_add_u32 s8, s46, 0x100400
	s_addc_u32 s9, s47, 0
	s_add_u32 s10, s46, 0x100500
	s_addc_u32 s11, s47, 0
	s_add_u32 s12, s46, 0x100600
	s_addc_u32 s13, s47, 0
	s_add_u32 s16, s46, 0x100700
	s_addc_u32 s17, s47, 0
	s_add_u32 s18, s46, 0x100800
	s_addc_u32 s19, s47, 0
	s_add_u32 s20, s46, 0x100900
	s_addc_u32 s21, s47, 0
	s_add_u32 s22, s46, 0x100a00
	s_addc_u32 s23, s47, 0
	s_add_u32 s24, s46, 0x100b00
	s_addc_u32 s25, s47, 0
	s_add_u32 s28, s46, 0x100c00
	s_addc_u32 s29, s47, 0
	s_add_u32 s30, s46, 0x100d00
	s_addc_u32 s31, s47, 0
	s_add_u32 s34, s46, 0x100e00
	s_addc_u32 s35, s47, 0
	s_add_u32 s36, s46, 0x100f00
	s_addc_u32 s37, s47, 0
	s_add_u32 s48, s46, 0x101000
	s_addc_u32 s49, s47, 0
	s_add_u32 s50, s46, 0x101100
	s_addc_u32 s51, s47, 0
	s_add_u32 s52, s46, 0x101200
	s_addc_u32 s53, s47, 0
	s_add_u32 s54, s46, 0x101300
	s_mul_i32 s26, s75, s81
	s_addc_u32 s55, s47, 0
	s_mul_i32 s26, s26, s74
	s_mov_b32 s27, 1
	s_mov_b64 s[6:7], 0
	s_waitcnt lgkmcnt(0)
	v_mov_b64_e32 v[0:1], s[8:9]
	v_mov_b64_e32 v[2:3], s[10:11]
	v_mov_b64_e32 v[4:5], s[12:13]
	v_mov_b64_e32 v[6:7], s[16:17]
	v_mov_b64_e32 v[8:9], s[18:19]
	v_mov_b64_e32 v[10:11], s[20:21]
	v_mov_b64_e32 v[12:13], s[22:23]
	v_mov_b64_e32 v[14:15], s[24:25]
	v_mov_b64_e32 v[16:17], s[28:29]
	v_mov_b64_e32 v[18:19], s[30:31]
	v_mov_b64_e32 v[20:21], s[34:35]
	v_mov_b64_e32 v[22:23], s[36:37]
	v_mov_b64_e32 v[24:25], s[48:49]
	v_mov_b64_e32 v[26:27], s[50:51]
	v_mov_b64_e32 v[28:29], s[52:53]
	v_mov_b64_e32 v[30:31], s[54:55]
	s_branch .LBB0_408

; __device__ __forceinline__ unsigned xb_ld(unsigned* p)              { return __hip_atomic_load(p, __ATOMIC_RELAXED, __HIP_MEMORY_SCOPE_AGENT); }
; __device__ __forceinline__ unsigned xb_add(unsigned* p, unsigned v) { return __hip_atomic_fetch_add(p, v, __ATOMIC_RELAXED, __HIP_MEMORY_SCOPE_AGENT); }
; __device__ __forceinline__ void xcd_barrier_complete(unsigned* bar, unsigned x, unsigned& nloc, unsigned& nx) {
;     const unsigned G = gridDim.x * gridDim.y * gridDim.z;
;     unsigned sum, cnt, mine, sp = 0u;
;     for (;;) {
;         sum = 0u; cnt = 0u; mine = 0u;
; #pragma unroll
;         for (unsigned j = 0; j < 16; ++j) { const unsigned c = xb_ld(&bar[XB_XCNT(j)]); sum += c; cnt += (c > 0u) ? 1u : 0u; mine = (j == x) ? c : mine; }
; __device__ __forceinline__ void xcd_barrier(const XcdBarrier& b) {
;     asm volatile("s_waitcnt vmcnt(0)" ::: "memory");
;     __syncthreads();
;     int t0_ = threadIdx.x; asm volatile("" : "+v"(t0_));
;     if (t0_ == 0) {
;         unsigned* bar = b.bar;
;         __builtin_amdgcn_s_waitcnt(0);
;         unsigned nloc = b.st[0], nx = b.st[1];
;         if (nloc == 0u) { xcd_barrier_complete(bar, b.x, nloc, nx); b.st[0] = nloc; b.st[1] = nx; }
;         const unsigned old = xb_add(&bar[XB_XSUB(b.x)], 1u);
.LBB0_570:
	s_or_b64 exec, exec, s[2:3]
	s_mov_b64 s[48:49], s[72:73]
	s_getreg_b32 s2, hwreg(HW_REG_XCC_ID, 0, 4)
	s_waitcnt vmcnt(0)
	v_mov_b32_e32 v0, v154
	s_waitcnt lgkmcnt(0)
	s_barrier
	s_nop 0
	v_cmp_eq_u32_e32 vcc, 0, v0
	s_and_saveexec_b64 s[46:47], vcc
	s_cbranch_execz .LBB0_614
	s_add_i32 s3, 0, 0x21000
	v_mov_b32_e32 v0, s3
	s_waitcnt vmcnt(0) expcnt(0) lgkmcnt(0)
	buffer_wbl2 sc1
	ds_read_b32 v2, v0
	s_add_i32 s3, 0, 0x21004
	v_mov_b32_e32 v0, s3
	ds_read_b32 v0, v0
	s_and_b32 s15, s2, 15
	s_waitcnt lgkmcnt(1)
	v_cmp_ne_u32_e32 vcc, 0, v2
	s_cbranch_vccnz .LBB0_585
	s_add_u32 s2, s48, 0x100200
	s_addc_u32 s3, s49, 0
	s_add_u32 s8, s48, 0x100400
	s_addc_u32 s9, s49, 0
	s_add_u32 s10, s48, 0x100500
	s_addc_u32 s11, s49, 0
	s_add_u32 s12, s48, 0x100600
	s_addc_u32 s13, s49, 0
	s_add_u32 s16, s48, 0x100700
	s_addc_u32 s17, s49, 0
	s_add_u32 s18, s48, 0x100800
	s_addc_u32 s19, s49, 0
	s_add_u32 s20, s48, 0x100900
	s_addc_u32 s21, s49, 0
	s_add_u32 s22, s48, 0x100a00
	s_addc_u32 s23, s49, 0
	s_add_u32 s24, s48, 0x100b00
	s_addc_u32 s25, s49, 0
	s_add_u32 s28, s48, 0x100c00
	s_addc_u32 s29, s49, 0
	s_add_u32 s30, s48, 0x100d00
	s_addc_u32 s31, s49, 0
	s_add_u32 s34, s48, 0x100e00
	s_addc_u32 s35, s49, 0
	s_add_u32 s36, s48, 0x100f00
	s_addc_u32 s37, s49, 0
	s_add_u32 s50, s48, 0x101000
	s_addc_u32 s51, s49, 0
	s_add_u32 s52, s48, 0x101100
	s_addc_u32 s53, s49, 0
	s_add_u32 s54, s48, 0x101200
	s_addc_u32 s55, s49, 0
	s_add_u32 s56, s48, 0x101300
	s_mul_i32 s26, s75, s81
	s_addc_u32 s57, s49, 0
	s_mul_i32 s26, s26, s74
	s_mov_b32 s27, 1
	s_mov_b64 s[6:7], 0
	s_waitcnt lgkmcnt(0)
	v_mov_b64_e32 v[0:1], s[8:9]
	v_mov_b64_e32 v[2:3], s[10:11]
	v_mov_b64_e32 v[4:5], s[12:13]
	v_mov_b64_e32 v[6:7], s[16:17]
	v_mov_b64_e32 v[8:9], s[18:19]
	v_mov_b64_e32 v[10:11], s[20:21]
	v_mov_b64_e32 v[12:13], s[22:23]
	v_mov_b64_e32 v[14:15], s[24:25]
	v_mov_b64_e32 v[16:17], s[28:29]
	v_mov_b64_e32 v[18:19], s[30:31]
	v_mov_b64_e32 v[20:21], s[34:35]
	v_mov_b64_e32 v[22:23], s[36:37]
	v_mov_b64_e32 v[24:25], s[50:51]
	v_mov_b64_e32 v[26:27], s[52:53]
	v_mov_b64_e32 v[28:29], s[54:55]
	v_mov_b64_e32 v[30:31], s[56:57]
	s_branch .LBB0_575

; __device__ __forceinline__ unsigned xb_ld(unsigned* p)              { return __hip_atomic_load(p, __ATOMIC_RELAXED, __HIP_MEMORY_SCOPE_AGENT); }
; __device__ __forceinline__ unsigned xb_add(unsigned* p, unsigned v) { return __hip_atomic_fetch_add(p, v, __ATOMIC_RELAXED, __HIP_MEMORY_SCOPE_AGENT); }
; __device__ __forceinline__ void xcd_barrier_complete(unsigned* bar, unsigned x, unsigned& nloc, unsigned& nx) {
;     const unsigned G = gridDim.x * gridDim.y * gridDim.z;
;     unsigned sum, cnt, mine, sp = 0u;
;     for (;;) {
;         sum = 0u; cnt = 0u; mine = 0u;
; #pragma unroll
;         for (unsigned j = 0; j < 16; ++j) { const unsigned c = xb_ld(&bar[XB_XCNT(j)]); sum += c; cnt += (c > 0u) ? 1u : 0u; mine = (j == x) ? c : mine; }
; __device__ __forceinline__ void xcd_barrier(const XcdBarrier& b) {
;     asm volatile("s_waitcnt vmcnt(0)" ::: "memory");
;     __syncthreads();
;     int t0_ = threadIdx.x; asm volatile("" : "+v"(t0_));
;     if (t0_ == 0) {
;         unsigned* bar = b.bar;
;         __builtin_amdgcn_s_waitcnt(0);
;         unsigned nloc = b.st[0], nx = b.st[1];
;         if (nloc == 0u) { xcd_barrier_complete(bar, b.x, nloc, nx); b.st[0] = nloc; b.st[1] = nx; }
;         const unsigned old = xb_add(&bar[XB_XSUB(b.x)], 1u);
.LBB0_650:
	s_mov_b64 s[48:49], s[72:73]
	s_getreg_b32 s2, hwreg(HW_REG_XCC_ID, 0, 4)
	s_waitcnt vmcnt(0)
	v_mov_b32_e32 v0, v154
	s_waitcnt lgkmcnt(0)
	s_barrier
	s_nop 0
	v_cmp_eq_u32_e32 vcc, 0, v0
	s_and_saveexec_b64 s[46:47], vcc
	s_cbranch_execz .LBB0_694
	s_add_i32 s3, 0, 0x21000
	v_mov_b32_e32 v0, s3
	s_waitcnt vmcnt(0) expcnt(0) lgkmcnt(0)
	buffer_wbl2 sc1
	ds_read_b32 v2, v0
	s_add_i32 s3, 0, 0x21004
	v_mov_b32_e32 v0, s3
	ds_read_b32 v0, v0
	s_and_b32 s15, s2, 15
	s_waitcnt lgkmcnt(1)
	v_cmp_ne_u32_e32 vcc, 0, v2
	s_cbranch_vccnz .LBB0_665
	s_add_u32 s2, s48, 0x100200
	s_addc_u32 s3, s49, 0
	s_add_u32 s8, s48, 0x100400
	s_addc_u32 s9, s49, 0
	s_add_u32 s10, s48, 0x100500
	s_addc_u32 s11, s49, 0
	s_add_u32 s12, s48, 0x100600
	s_addc_u32 s13, s49, 0
	s_add_u32 s16, s48, 0x100700
	s_addc_u32 s17, s49, 0
	s_add_u32 s18, s48, 0x100800
	s_addc_u32 s19, s49, 0
	s_add_u32 s20, s48, 0x100900
	s_addc_u32 s21, s49, 0
	s_add_u32 s22, s48, 0x100a00
	s_addc_u32 s23, s49, 0
	s_add_u32 s24, s48, 0x100b00
	s_addc_u32 s25, s49, 0
	s_add_u32 s28, s48, 0x100c00
	s_addc_u32 s29, s49, 0
	s_add_u32 s30, s48, 0x100d00
	s_addc_u32 s31, s49, 0
	s_add_u32 s34, s48, 0x100e00
	s_addc_u32 s35, s49, 0
	s_add_u32 s36, s48, 0x100f00
	s_addc_u32 s37, s49, 0
	s_add_u32 s50, s48, 0x101000
	s_addc_u32 s51, s49, 0
	s_add_u32 s52, s48, 0x101100
	s_addc_u32 s53, s49, 0
	s_add_u32 s54, s48, 0x101200
	s_addc_u32 s55, s49, 0
	s_add_u32 s56, s48, 0x101300
	s_mul_i32 s26, s75, s81
	s_addc_u32 s57, s49, 0
	s_mul_i32 s26, s26, s74
	s_mov_b32 s27, 1
	s_mov_b64 s[6:7], 0
	s_waitcnt lgkmcnt(0)
	v_mov_b64_e32 v[0:1], s[8:9]
	v_mov_b64_e32 v[2:3], s[10:11]
	v_mov_b64_e32 v[4:5], s[12:13]
	v_mov_b64_e32 v[6:7], s[16:17]
	v_mov_b64_e32 v[8:9], s[18:19]
	v_mov_b64_e32 v[10:11], s[20:21]
	v_mov_b64_e32 v[12:13], s[22:23]
	v_mov_b64_e32 v[14:15], s[24:25]
	v_mov_b64_e32 v[16:17], s[28:29]
	v_mov_b64_e32 v[18:19], s[30:31]
	v_mov_b64_e32 v[20:21], s[34:35]
	v_mov_b64_e32 v[22:23], s[36:37]
	v_mov_b64_e32 v[24:25], s[50:51]
	v_mov_b64_e32 v[26:27], s[52:53]
	v_mov_b64_e32 v[28:29], s[54:55]
	v_mov_b64_e32 v[30:31], s[56:57]
	s_branch .LBB0_655

; __device__ __forceinline__ unsigned xb_ld(unsigned* p)              { return __hip_atomic_load(p, __ATOMIC_RELAXED, __HIP_MEMORY_SCOPE_AGENT); }
; __device__ __forceinline__ unsigned xb_add(unsigned* p, unsigned v) { return __hip_atomic_fetch_add(p, v, __ATOMIC_RELAXED, __HIP_MEMORY_SCOPE_AGENT); }
; __device__ __forceinline__ void xcd_barrier_complete(unsigned* bar, unsigned x, unsigned& nloc, unsigned& nx) {
;     const unsigned G = gridDim.x * gridDim.y * gridDim.z;
;     unsigned sum, cnt, mine, sp = 0u;
;     for (;;) {
;         sum = 0u; cnt = 0u; mine = 0u;
; #pragma unroll
;         for (unsigned j = 0; j < 16; ++j) { const unsigned c = xb_ld(&bar[XB_XCNT(j)]); sum += c; cnt += (c > 0u) ? 1u : 0u; mine = (j == x) ? c : mine; }
; __device__ __forceinline__ void xcd_barrier(const XcdBarrier& b) {
;     asm volatile("s_waitcnt vmcnt(0)" ::: "memory");
;     __syncthreads();
;     int t0_ = threadIdx.x; asm volatile("" : "+v"(t0_));
;     if (t0_ == 0) {
;         unsigned* bar = b.bar;
;         __builtin_amdgcn_s_waitcnt(0);
;         unsigned nloc = b.st[0], nx = b.st[1];
;         if (nloc == 0u) { xcd_barrier_complete(bar, b.x, nloc, nx); b.st[0] = nloc; b.st[1] = nx; }
;         const unsigned old = xb_add(&bar[XB_XSUB(b.x)], 1u);
.LBB0_710:
	s_mov_b64 s[48:49], s[72:73]
	s_getreg_b32 s6, hwreg(HW_REG_XCC_ID, 0, 4)
	s_waitcnt vmcnt(0)
	v_mov_b32_e32 v0, v154
	s_barrier
	s_nop 0
	v_cmp_eq_u32_e32 vcc, 0, v0
	s_and_saveexec_b64 s[46:47], vcc
	s_cbranch_execz .LBB0_754
	s_add_i32 s7, 0, 0x21000
	v_mov_b32_e32 v0, s7
	s_waitcnt vmcnt(0) expcnt(0) lgkmcnt(0)
	buffer_wbl2 sc1
	ds_read_b32 v2, v0
	s_add_i32 s7, 0, 0x21004
	v_mov_b32_e32 v0, s7
	ds_read_b32 v0, v0
	s_and_b32 s15, s6, 15
	s_waitcnt lgkmcnt(1)
	v_cmp_ne_u32_e32 vcc, 0, v2
	s_cbranch_vccnz .LBB0_725
	s_add_u32 s6, s48, 0x100200
	s_addc_u32 s7, s49, 0
	s_add_u32 s10, s48, 0x100400
	s_addc_u32 s11, s49, 0
	s_add_u32 s12, s48, 0x100500
	s_addc_u32 s13, s49, 0
	s_add_u32 s16, s48, 0x100600
	s_addc_u32 s17, s49, 0
	s_add_u32 s18, s48, 0x100700
	s_addc_u32 s19, s49, 0
	s_add_u32 s20, s48, 0x100800
	s_addc_u32 s21, s49, 0
	s_add_u32 s22, s48, 0x100900
	s_addc_u32 s23, s49, 0
	s_add_u32 s24, s48, 0x100a00
	s_addc_u32 s25, s49, 0
	s_add_u32 s26, s48, 0x100b00
	s_addc_u32 s27, s49, 0
	s_add_u32 s30, s48, 0x100c00
	s_addc_u32 s31, s49, 0
	s_add_u32 s34, s48, 0x100d00
	s_addc_u32 s35, s49, 0
	s_add_u32 s36, s48, 0x100e00
	s_addc_u32 s37, s49, 0
	s_add_u32 s38, s48, 0x100f00
	s_addc_u32 s39, s49, 0
	s_add_u32 s50, s48, 0x101000
	s_addc_u32 s51, s49, 0
	s_add_u32 s52, s48, 0x101100
	s_addc_u32 s53, s49, 0
	s_add_u32 s54, s48, 0x101200
	s_addc_u32 s55, s49, 0
	s_add_u32 s56, s48, 0x101300
	s_mul_i32 s28, s75, s81
	s_addc_u32 s57, s49, 0
	s_mul_i32 s28, s28, s74
	s_mov_b32 s29, 1
	s_mov_b64 s[8:9], 0
	s_waitcnt lgkmcnt(0)
	v_mov_b64_e32 v[0:1], s[10:11]
	v_mov_b64_e32 v[2:3], s[12:13]
	v_mov_b64_e32 v[4:5], s[16:17]
	v_mov_b64_e32 v[6:7], s[18:19]
	v_mov_b64_e32 v[8:9], s[20:21]
	v_mov_b64_e32 v[10:11], s[22:23]
	v_mov_b64_e32 v[12:13], s[24:25]
	v_mov_b64_e32 v[14:15], s[26:27]
	v_mov_b64_e32 v[16:17], s[30:31]
	v_mov_b64_e32 v[18:19], s[34:35]
	v_mov_b64_e32 v[20:21], s[36:37]
	v_mov_b64_e32 v[22:23], s[38:39]
	v_mov_b64_e32 v[24:25], s[50:51]
	v_mov_b64_e32 v[26:27], s[52:53]
	v_mov_b64_e32 v[28:29], s[54:55]
	v_mov_b64_e32 v[30:31], s[56:57]
	s_branch .LBB0_715

; __device__ __forceinline__ unsigned xb_ld(unsigned* p)              { return __hip_atomic_load(p, __ATOMIC_RELAXED, __HIP_MEMORY_SCOPE_AGENT); }
; __device__ __forceinline__ unsigned xb_add(unsigned* p, unsigned v) { return __hip_atomic_fetch_add(p, v, __ATOMIC_RELAXED, __HIP_MEMORY_SCOPE_AGENT); }
; __device__ __forceinline__ void xcd_barrier_complete(unsigned* bar, unsigned x, unsigned& nloc, unsigned& nx) {
;     const unsigned G = gridDim.x * gridDim.y * gridDim.z;
;     unsigned sum, cnt, mine, sp = 0u;
;     for (;;) {
;         sum = 0u; cnt = 0u; mine = 0u;
; #pragma unroll
;         for (unsigned j = 0; j < 16; ++j) { const unsigned c = xb_ld(&bar[XB_XCNT(j)]); sum += c; cnt += (c > 0u) ? 1u : 0u; mine = (j == x) ? c : mine; }
; __device__ __forceinline__ void xcd_barrier(const XcdBarrier& b) {
;     asm volatile("s_waitcnt vmcnt(0)" ::: "memory");
;     __syncthreads();
;     int t0_ = threadIdx.x; asm volatile("" : "+v"(t0_));
;     if (t0_ == 0) {
;         unsigned* bar = b.bar;
;         __builtin_amdgcn_s_waitcnt(0);
;         unsigned nloc = b.st[0], nx = b.st[1];
;         if (nloc == 0u) { xcd_barrier_complete(bar, b.x, nloc, nx); b.st[0] = nloc; b.st[1] = nx; }
;         const unsigned old = xb_add(&bar[XB_XSUB(b.x)], 1u);
.LBB0_823:
	s_mov_b64 s[48:49], s[72:73]
	s_getreg_b32 s8, hwreg(HW_REG_XCC_ID, 0, 4)
	s_waitcnt vmcnt(0)
	v_mov_b32_e32 v0, v154
	s_waitcnt lgkmcnt(0)
	s_barrier
	s_nop 0
	v_cmp_eq_u32_e32 vcc, 0, v0
	s_and_saveexec_b64 s[46:47], vcc
	s_cbranch_execz .LBB0_867
	s_add_i32 s9, 0, 0x21000
	v_mov_b32_e32 v0, s9
	s_waitcnt vmcnt(0) expcnt(0) lgkmcnt(0)
	buffer_wbl2 sc1
	ds_read_b32 v2, v0
	s_add_i32 s9, 0, 0x21004
	v_mov_b32_e32 v0, s9
	ds_read_b32 v0, v0
	s_and_b32 s15, s8, 15
	s_waitcnt lgkmcnt(1)
	v_cmp_ne_u32_e32 vcc, 0, v2
	s_cbranch_vccnz .LBB0_838
	s_add_u32 s8, s48, 0x100200
	s_addc_u32 s9, s49, 0
	s_add_u32 s12, s48, 0x100400
	s_addc_u32 s13, s49, 0
	s_add_u32 s16, s48, 0x100500
	s_addc_u32 s17, s49, 0
	s_add_u32 s18, s48, 0x100600
	s_addc_u32 s19, s49, 0
	s_add_u32 s20, s48, 0x100700
	s_addc_u32 s21, s49, 0
	s_add_u32 s22, s48, 0x100800
	s_addc_u32 s23, s49, 0
	s_add_u32 s24, s48, 0x100900
	s_addc_u32 s25, s49, 0
	s_add_u32 s26, s48, 0x100a00
	s_addc_u32 s27, s49, 0
	s_add_u32 s28, s48, 0x100b00
	s_addc_u32 s29, s49, 0
	s_add_u32 s34, s48, 0x100c00
	s_addc_u32 s35, s49, 0
	s_add_u32 s36, s48, 0x100d00
	s_addc_u32 s37, s49, 0
	s_add_u32 s38, s48, 0x100e00
	s_addc_u32 s39, s49, 0
	s_add_u32 s40, s48, 0x100f00
	s_addc_u32 s41, s49, 0
	s_add_u32 s50, s48, 0x101000
	s_addc_u32 s51, s49, 0
	s_add_u32 s52, s48, 0x101100
	s_addc_u32 s53, s49, 0
	s_add_u32 s54, s48, 0x101200
	s_addc_u32 s55, s49, 0
	s_add_u32 s56, s48, 0x101300
	s_mul_i32 s30, s75, s81
	s_addc_u32 s57, s49, 0
	s_mul_i32 s30, s30, s74
	s_mov_b32 s31, 1
	s_mov_b64 s[10:11], 0
	s_waitcnt lgkmcnt(0)
	v_mov_b64_e32 v[0:1], s[12:13]
	v_mov_b64_e32 v[2:3], s[16:17]
	v_mov_b64_e32 v[4:5], s[18:19]
	v_mov_b64_e32 v[6:7], s[20:21]
	v_mov_b64_e32 v[8:9], s[22:23]
	v_mov_b64_e32 v[10:11], s[24:25]
	v_mov_b64_e32 v[12:13], s[26:27]
	v_mov_b64_e32 v[14:15], s[28:29]
	v_mov_b64_e32 v[16:17], s[34:35]
	v_mov_b64_e32 v[18:19], s[36:37]
	v_mov_b64_e32 v[20:21], s[38:39]
	v_mov_b64_e32 v[22:23], s[40:41]
	v_mov_b64_e32 v[24:25], s[50:51]
	v_mov_b64_e32 v[26:27], s[52:53]
	v_mov_b64_e32 v[28:29], s[54:55]
	v_mov_b64_e32 v[30:31], s[56:57]
	s_branch .LBB0_828

; __device__ __forceinline__ unsigned xb_ld(unsigned* p)              { return __hip_atomic_load(p, __ATOMIC_RELAXED, __HIP_MEMORY_SCOPE_AGENT); }
; __device__ __forceinline__ unsigned xb_add(unsigned* p, unsigned v) { return __hip_atomic_fetch_add(p, v, __ATOMIC_RELAXED, __HIP_MEMORY_SCOPE_AGENT); }
; __device__ __forceinline__ void xcd_barrier_complete(unsigned* bar, unsigned x, unsigned& nloc, unsigned& nx) {
;     const unsigned G = gridDim.x * gridDim.y * gridDim.z;
;     unsigned sum, cnt, mine, sp = 0u;
;     for (;;) {
;         sum = 0u; cnt = 0u; mine = 0u;
; #pragma unroll
;         for (unsigned j = 0; j < 16; ++j) { const unsigned c = xb_ld(&bar[XB_XCNT(j)]); sum += c; cnt += (c > 0u) ? 1u : 0u; mine = (j == x) ? c : mine; }
; __device__ __forceinline__ void xcd_barrier(const XcdBarrier& b) {
;     asm volatile("s_waitcnt vmcnt(0)" ::: "memory");
;     __syncthreads();
;     int t0_ = threadIdx.x; asm volatile("" : "+v"(t0_));
;     if (t0_ == 0) {
;         unsigned* bar = b.bar;
;         __builtin_amdgcn_s_waitcnt(0);
;         unsigned nloc = b.st[0], nx = b.st[1];
;         if (nloc == 0u) { xcd_barrier_complete(bar, b.x, nloc, nx); b.st[0] = nloc; b.st[1] = nx; }
;         const unsigned old = xb_add(&bar[XB_XSUB(b.x)], 1u);
.LBB0_883:
	s_mov_b64 s[48:49], s[72:73]
	s_getreg_b32 s8, hwreg(HW_REG_XCC_ID, 0, 4)
	s_waitcnt vmcnt(0)
	v_mov_b32_e32 v0, v154
	s_barrier
	s_nop 0
	v_cmp_eq_u32_e32 vcc, 0, v0
	s_and_saveexec_b64 s[46:47], vcc
	s_cbranch_execz .LBB0_927
	s_add_i32 s9, 0, 0x21000
	v_mov_b32_e32 v0, s9
	s_waitcnt vmcnt(0) expcnt(0) lgkmcnt(0)
	buffer_wbl2 sc1
	ds_read_b32 v2, v0
	s_add_i32 s9, 0, 0x21004
	v_mov_b32_e32 v0, s9
	ds_read_b32 v0, v0
	s_and_b32 s15, s8, 15
	s_waitcnt lgkmcnt(1)
	v_cmp_ne_u32_e32 vcc, 0, v2
	s_cbranch_vccnz .LBB0_898
	s_add_u32 s8, s48, 0x100200
	s_addc_u32 s9, s49, 0
	s_add_u32 s12, s48, 0x100400
	s_addc_u32 s13, s49, 0
	s_add_u32 s16, s48, 0x100500
	s_addc_u32 s17, s49, 0
	s_add_u32 s18, s48, 0x100600
	s_addc_u32 s19, s49, 0
	s_add_u32 s20, s48, 0x100700
	s_addc_u32 s21, s49, 0
	s_add_u32 s22, s48, 0x100800
	s_addc_u32 s23, s49, 0
	s_add_u32 s24, s48, 0x100900
	s_addc_u32 s25, s49, 0
	s_add_u32 s26, s48, 0x100a00
	s_addc_u32 s27, s49, 0
	s_add_u32 s28, s48, 0x100b00
	s_addc_u32 s29, s49, 0
	s_add_u32 s34, s48, 0x100c00
	s_addc_u32 s35, s49, 0
	s_add_u32 s36, s48, 0x100d00
	s_addc_u32 s37, s49, 0
	s_add_u32 s38, s48, 0x100e00
	s_addc_u32 s39, s49, 0
	s_add_u32 s40, s48, 0x100f00
	s_addc_u32 s41, s49, 0
	s_add_u32 s50, s48, 0x101000
	s_addc_u32 s51, s49, 0
	s_add_u32 s52, s48, 0x101100
	s_addc_u32 s53, s49, 0
	s_add_u32 s54, s48, 0x101200
	s_addc_u32 s55, s49, 0
	s_add_u32 s56, s48, 0x101300
	s_mul_i32 s30, s75, s81
	s_addc_u32 s57, s49, 0
	s_mul_i32 s30, s30, s74
	s_mov_b32 s31, 1
	s_mov_b64 s[10:11], 0
	s_waitcnt lgkmcnt(0)
	v_mov_b64_e32 v[0:1], s[12:13]
	v_mov_b64_e32 v[2:3], s[16:17]
	v_mov_b64_e32 v[4:5], s[18:19]
	v_mov_b64_e32 v[6:7], s[20:21]
	v_mov_b64_e32 v[8:9], s[22:23]
	v_mov_b64_e32 v[10:11], s[24:25]
	v_mov_b64_e32 v[12:13], s[26:27]
	v_mov_b64_e32 v[14:15], s[28:29]
	v_mov_b64_e32 v[16:17], s[34:35]
	v_mov_b64_e32 v[18:19], s[36:37]
	v_mov_b64_e32 v[20:21], s[38:39]
	v_mov_b64_e32 v[22:23], s[40:41]
	v_mov_b64_e32 v[24:25], s[50:51]
	v_mov_b64_e32 v[26:27], s[52:53]
	v_mov_b64_e32 v[28:29], s[54:55]
	v_mov_b64_e32 v[30:31], s[56:57]
	s_branch .LBB0_888

; __device__ __forceinline__ unsigned xb_ld(unsigned* p)              { return __hip_atomic_load(p, __ATOMIC_RELAXED, __HIP_MEMORY_SCOPE_AGENT); }
; __device__ __forceinline__ unsigned xb_add(unsigned* p, unsigned v) { return __hip_atomic_fetch_add(p, v, __ATOMIC_RELAXED, __HIP_MEMORY_SCOPE_AGENT); }
; __device__ __forceinline__ void xcd_barrier_complete(unsigned* bar, unsigned x, unsigned& nloc, unsigned& nx) {
;     const unsigned G = gridDim.x * gridDim.y * gridDim.z;
;     unsigned sum, cnt, mine, sp = 0u;
;     for (;;) {
;         sum = 0u; cnt = 0u; mine = 0u;
; #pragma unroll
;         for (unsigned j = 0; j < 16; ++j) { const unsigned c = xb_ld(&bar[XB_XCNT(j)]); sum += c; cnt += (c > 0u) ? 1u : 0u; mine = (j == x) ? c : mine; }
; __device__ __forceinline__ void xcd_barrier(const XcdBarrier& b) {
;     asm volatile("s_waitcnt vmcnt(0)" ::: "memory");
;     __syncthreads();
;     int t0_ = threadIdx.x; asm volatile("" : "+v"(t0_));
;     if (t0_ == 0) {
;         unsigned* bar = b.bar;
;         __builtin_amdgcn_s_waitcnt(0);
;         unsigned nloc = b.st[0], nx = b.st[1];
;         if (nloc == 0u) { xcd_barrier_complete(bar, b.x, nloc, nx); b.st[0] = nloc; b.st[1] = nx; }
;         const unsigned old = xb_add(&bar[XB_XSUB(b.x)], 1u);
.LBB0_1117:
	s_mov_b64 s[46:47], s[72:73]
	s_getreg_b32 s4, hwreg(HW_REG_XCC_ID, 0, 4)
	s_waitcnt vmcnt(0)
	v_mov_b32_e32 v0, v154
	s_barrier
	s_nop 0
	v_cmp_eq_u32_e32 vcc, 0, v0
	s_and_saveexec_b64 s[40:41], vcc
	s_cbranch_execz .LBB0_1161
	s_add_i32 s5, 0, 0x21000
	v_mov_b32_e32 v0, s5
	s_waitcnt vmcnt(0) expcnt(0) lgkmcnt(0)
	buffer_wbl2 sc1
	ds_read_b32 v2, v0
	s_add_i32 s5, 0, 0x21004
	v_mov_b32_e32 v0, s5
	ds_read_b32 v0, v0
	s_and_b32 s15, s4, 15
	s_waitcnt lgkmcnt(1)
	v_cmp_ne_u32_e32 vcc, 0, v2
	s_cbranch_vccnz .LBB0_1132
	s_add_u32 s4, s46, 0x100200
	s_addc_u32 s5, s47, 0
	s_add_u32 s10, s46, 0x100400
	s_addc_u32 s11, s47, 0
	s_add_u32 s12, s46, 0x100500
	s_addc_u32 s13, s47, 0
	s_add_u32 s16, s46, 0x100600
	s_addc_u32 s17, s47, 0
	s_add_u32 s18, s46, 0x100700
	s_addc_u32 s19, s47, 0
	s_add_u32 s20, s46, 0x100800
	s_addc_u32 s21, s47, 0
	s_add_u32 s22, s46, 0x100900
	s_addc_u32 s23, s47, 0
	s_add_u32 s24, s46, 0x100a00
	s_addc_u32 s25, s47, 0
	s_add_u32 s26, s46, 0x100b00
	s_addc_u32 s27, s47, 0
	s_add_u32 s30, s46, 0x100c00
	s_addc_u32 s31, s47, 0
	s_add_u32 s34, s46, 0x100d00
	s_addc_u32 s35, s47, 0
	s_add_u32 s36, s46, 0x100e00
	s_addc_u32 s37, s47, 0
	s_add_u32 s38, s46, 0x100f00
	s_addc_u32 s39, s47, 0
	s_add_u32 s48, s46, 0x101000
	s_addc_u32 s49, s47, 0
	s_add_u32 s50, s46, 0x101100
	s_addc_u32 s51, s47, 0
	s_add_u32 s52, s46, 0x101200
	s_addc_u32 s53, s47, 0
	s_add_u32 s54, s46, 0x101300
	s_mul_i32 s28, s75, s81
	s_addc_u32 s55, s47, 0
	s_mul_i32 s28, s28, s74
	s_mov_b32 s29, 1
	s_mov_b64 s[8:9], 0
	s_waitcnt lgkmcnt(0)
	v_mov_b64_e32 v[0:1], s[10:11]
	v_mov_b64_e32 v[2:3], s[12:13]
	v_mov_b64_e32 v[4:5], s[16:17]
	v_mov_b64_e32 v[6:7], s[18:19]
	v_mov_b64_e32 v[8:9], s[20:21]
	v_mov_b64_e32 v[10:11], s[22:23]
	v_mov_b64_e32 v[12:13], s[24:25]
	v_mov_b64_e32 v[14:15], s[26:27]
	v_mov_b64_e32 v[16:17], s[30:31]
	v_mov_b64_e32 v[18:19], s[34:35]
	v_mov_b64_e32 v[20:21], s[36:37]
	v_mov_b64_e32 v[22:23], s[38:39]
	v_mov_b64_e32 v[24:25], s[48:49]
	v_mov_b64_e32 v[26:27], s[50:51]
	v_mov_b64_e32 v[28:29], s[52:53]
	v_mov_b64_e32 v[30:31], s[54:55]
	s_branch .LBB0_1122

; __device__ __forceinline__ unsigned xb_ld(unsigned* p)              { return __hip_atomic_load(p, __ATOMIC_RELAXED, __HIP_MEMORY_SCOPE_AGENT); }
; __device__ __forceinline__ unsigned xb_add(unsigned* p, unsigned v) { return __hip_atomic_fetch_add(p, v, __ATOMIC_RELAXED, __HIP_MEMORY_SCOPE_AGENT); }
; __device__ __forceinline__ void xcd_barrier_complete(unsigned* bar, unsigned x, unsigned& nloc, unsigned& nx) {
;     const unsigned G = gridDim.x * gridDim.y * gridDim.z;
;     unsigned sum, cnt, mine, sp = 0u;
;     for (;;) {
;         sum = 0u; cnt = 0u; mine = 0u;
; #pragma unroll
;         for (unsigned j = 0; j < 16; ++j) { const unsigned c = xb_ld(&bar[XB_XCNT(j)]); sum += c; cnt += (c > 0u) ? 1u : 0u; mine = (j == x) ? c : mine; }
; __device__ __forceinline__ void xcd_barrier(const XcdBarrier& b) {
;     asm volatile("s_waitcnt vmcnt(0)" ::: "memory");
;     __syncthreads();
;     int t0_ = threadIdx.x; asm volatile("" : "+v"(t0_));
;     if (t0_ == 0) {
;         unsigned* bar = b.bar;
;         __builtin_amdgcn_s_waitcnt(0);
;         unsigned nloc = b.st[0], nx = b.st[1];
;         if (nloc == 0u) { xcd_barrier_complete(bar, b.x, nloc, nx); b.st[0] = nloc; b.st[1] = nx; }
;         const unsigned old = xb_add(&bar[XB_XSUB(b.x)], 1u);
.LBB0_1282:
	s_or_b64 exec, exec, s[4:5]
	s_mov_b64 s[44:45], s[72:73]
	s_getreg_b32 s4, hwreg(HW_REG_XCC_ID, 0, 4)
	s_waitcnt vmcnt(0)
	v_mov_b32_e32 v0, v154
	s_waitcnt lgkmcnt(0)
	s_barrier
	s_nop 0
	v_cmp_eq_u32_e32 vcc, 0, v0
	s_and_saveexec_b64 s[40:41], vcc
	s_cbranch_execz .LBB0_1326
	s_add_i32 s5, 0, 0x21000
	v_mov_b32_e32 v0, s5
	s_waitcnt vmcnt(0) expcnt(0) lgkmcnt(0)
	buffer_wbl2 sc1
	ds_read_b32 v2, v0
	s_add_i32 s5, 0, 0x21004
	v_mov_b32_e32 v0, s5
	ds_read_b32 v0, v0
	s_and_b32 s15, s4, 15
	s_waitcnt lgkmcnt(1)
	v_cmp_ne_u32_e32 vcc, 0, v2
	s_cbranch_vccnz .LBB0_1297
	s_add_u32 s4, s44, 0x100200
	s_addc_u32 s5, s45, 0
	s_add_u32 s10, s44, 0x100400
	s_addc_u32 s11, s45, 0
	s_add_u32 s12, s44, 0x100500
	s_addc_u32 s13, s45, 0
	s_add_u32 s16, s44, 0x100600
	s_addc_u32 s17, s45, 0
	s_add_u32 s18, s44, 0x100700
	s_addc_u32 s19, s45, 0
	s_add_u32 s20, s44, 0x100800
	s_addc_u32 s21, s45, 0
	s_add_u32 s22, s44, 0x100900
	s_addc_u32 s23, s45, 0
	s_add_u32 s24, s44, 0x100a00
	s_addc_u32 s25, s45, 0
	s_add_u32 s26, s44, 0x100b00
	s_addc_u32 s27, s45, 0
	s_add_u32 s30, s44, 0x100c00
	s_addc_u32 s31, s45, 0
	s_add_u32 s34, s44, 0x100d00
	s_addc_u32 s35, s45, 0
	s_add_u32 s36, s44, 0x100e00
	s_addc_u32 s37, s45, 0
	s_add_u32 s38, s44, 0x100f00
	s_addc_u32 s39, s45, 0
	s_add_u32 s46, s44, 0x101000
	s_addc_u32 s47, s45, 0
	s_add_u32 s48, s44, 0x101100
	s_addc_u32 s49, s45, 0
	s_add_u32 s50, s44, 0x101200
	s_addc_u32 s51, s45, 0
	s_add_u32 s52, s44, 0x101300
	s_mul_i32 s28, s75, s81
	s_addc_u32 s53, s45, 0
	s_mul_i32 s28, s28, s74
	s_mov_b32 s29, 1
	s_mov_b64 s[8:9], 0
	s_waitcnt lgkmcnt(0)
	v_mov_b64_e32 v[0:1], s[10:11]
	v_mov_b64_e32 v[2:3], s[12:13]
	v_mov_b64_e32 v[4:5], s[16:17]
	v_mov_b64_e32 v[6:7], s[18:19]
	v_mov_b64_e32 v[8:9], s[20:21]
	v_mov_b64_e32 v[10:11], s[22:23]
	v_mov_b64_e32 v[12:13], s[24:25]
	v_mov_b64_e32 v[14:15], s[26:27]
	v_mov_b64_e32 v[16:17], s[30:31]
	v_mov_b64_e32 v[18:19], s[34:35]
	v_mov_b64_e32 v[20:21], s[36:37]
	v_mov_b64_e32 v[22:23], s[38:39]
	v_mov_b64_e32 v[24:25], s[46:47]
	v_mov_b64_e32 v[26:27], s[48:49]
	v_mov_b64_e32 v[28:29], s[50:51]
	v_mov_b64_e32 v[30:31], s[52:53]
	s_branch .LBB0_1287

; __device__ __forceinline__ unsigned xb_ld(unsigned* p)              { return __hip_atomic_load(p, __ATOMIC_RELAXED, __HIP_MEMORY_SCOPE_AGENT); }
; __device__ __forceinline__ unsigned xb_add(unsigned* p, unsigned v) { return __hip_atomic_fetch_add(p, v, __ATOMIC_RELAXED, __HIP_MEMORY_SCOPE_AGENT); }
; __device__ __forceinline__ void xcd_barrier_complete(unsigned* bar, unsigned x, unsigned& nloc, unsigned& nx) {
;     const unsigned G = gridDim.x * gridDim.y * gridDim.z;
;     unsigned sum, cnt, mine, sp = 0u;
;     for (;;) {
;         sum = 0u; cnt = 0u; mine = 0u;
; #pragma unroll
;         for (unsigned j = 0; j < 16; ++j) { const unsigned c = xb_ld(&bar[XB_XCNT(j)]); sum += c; cnt += (c > 0u) ? 1u : 0u; mine = (j == x) ? c : mine; }
; __device__ __forceinline__ void xcd_barrier(const XcdBarrier& b) {
;     asm volatile("s_waitcnt vmcnt(0)" ::: "memory");
;     __syncthreads();
;     int t0_ = threadIdx.x; asm volatile("" : "+v"(t0_));
;     if (t0_ == 0) {
;         unsigned* bar = b.bar;
;         __builtin_amdgcn_s_waitcnt(0);
;         unsigned nloc = b.st[0], nx = b.st[1];
;         if (nloc == 0u) { xcd_barrier_complete(bar, b.x, nloc, nx); b.st[0] = nloc; b.st[1] = nx; }
;         const unsigned old = xb_add(&bar[XB_XSUB(b.x)], 1u);
.LBB0_1362:
	s_mov_b64 s[44:45], s[72:73]
	s_getreg_b32 s4, hwreg(HW_REG_XCC_ID, 0, 4)
	s_waitcnt vmcnt(0)
	v_mov_b32_e32 v0, v154
	s_waitcnt lgkmcnt(0)
	s_barrier
	s_nop 0
	v_cmp_eq_u32_e32 vcc, 0, v0
	s_and_saveexec_b64 s[40:41], vcc
	s_cbranch_execz .LBB0_1406
	s_add_i32 s5, 0, 0x21000
	v_mov_b32_e32 v0, s5
	s_waitcnt vmcnt(0) expcnt(0) lgkmcnt(0)
	buffer_wbl2 sc1
	ds_read_b32 v2, v0
	s_add_i32 s5, 0, 0x21004
	v_mov_b32_e32 v0, s5
	ds_read_b32 v0, v0
	s_and_b32 s15, s4, 15
	s_waitcnt lgkmcnt(1)
	v_cmp_ne_u32_e32 vcc, 0, v2
	s_cbranch_vccnz .LBB0_1377
	s_add_u32 s4, s44, 0x100200
	s_addc_u32 s5, s45, 0
	s_add_u32 s10, s44, 0x100400
	s_addc_u32 s11, s45, 0
	s_add_u32 s12, s44, 0x100500
	s_addc_u32 s13, s45, 0
	s_add_u32 s16, s44, 0x100600
	s_addc_u32 s17, s45, 0
	s_add_u32 s18, s44, 0x100700
	s_addc_u32 s19, s45, 0
	s_add_u32 s20, s44, 0x100800
	s_addc_u32 s21, s45, 0
	s_add_u32 s22, s44, 0x100900
	s_addc_u32 s23, s45, 0
	s_add_u32 s24, s44, 0x100a00
	s_addc_u32 s25, s45, 0
	s_add_u32 s26, s44, 0x100b00
	s_addc_u32 s27, s45, 0
	s_add_u32 s30, s44, 0x100c00
	s_addc_u32 s31, s45, 0
	s_add_u32 s34, s44, 0x100d00
	s_addc_u32 s35, s45, 0
	s_add_u32 s36, s44, 0x100e00
	s_addc_u32 s37, s45, 0
	s_add_u32 s38, s44, 0x100f00
	s_addc_u32 s39, s45, 0
	s_add_u32 s46, s44, 0x101000
	s_addc_u32 s47, s45, 0
	s_add_u32 s48, s44, 0x101100
	s_addc_u32 s49, s45, 0
	s_add_u32 s50, s44, 0x101200
	s_addc_u32 s51, s45, 0
	s_add_u32 s52, s44, 0x101300
	s_mul_i32 s28, s75, s81
	s_addc_u32 s53, s45, 0
	s_mul_i32 s28, s28, s74
	s_mov_b32 s29, 1
	s_mov_b64 s[8:9], 0
	s_waitcnt lgkmcnt(0)
	v_mov_b64_e32 v[0:1], s[10:11]
	v_mov_b64_e32 v[2:3], s[12:13]
	v_mov_b64_e32 v[4:5], s[16:17]
	v_mov_b64_e32 v[6:7], s[18:19]
	v_mov_b64_e32 v[8:9], s[20:21]
	v_mov_b64_e32 v[10:11], s[22:23]
	v_mov_b64_e32 v[12:13], s[24:25]
	v_mov_b64_e32 v[14:15], s[26:27]
	v_mov_b64_e32 v[16:17], s[30:31]
	v_mov_b64_e32 v[18:19], s[34:35]
	v_mov_b64_e32 v[20:21], s[36:37]
	v_mov_b64_e32 v[22:23], s[38:39]
	v_mov_b64_e32 v[24:25], s[46:47]
	v_mov_b64_e32 v[26:27], s[48:49]
	v_mov_b64_e32 v[28:29], s[50:51]
	v_mov_b64_e32 v[30:31], s[52:53]
	s_branch .LBB0_1367

; __device__ __forceinline__ unsigned xb_ld(unsigned* p)              { return __hip_atomic_load(p, __ATOMIC_RELAXED, __HIP_MEMORY_SCOPE_AGENT); }
; __device__ __forceinline__ unsigned xb_add(unsigned* p, unsigned v) { return __hip_atomic_fetch_add(p, v, __ATOMIC_RELAXED, __HIP_MEMORY_SCOPE_AGENT); }
; __device__ __forceinline__ void xcd_barrier_complete(unsigned* bar, unsigned x, unsigned& nloc, unsigned& nx) {
;     const unsigned G = gridDim.x * gridDim.y * gridDim.z;
;     unsigned sum, cnt, mine, sp = 0u;
;     for (;;) {
;         sum = 0u; cnt = 0u; mine = 0u;
; #pragma unroll
;         for (unsigned j = 0; j < 16; ++j) { const unsigned c = xb_ld(&bar[XB_XCNT(j)]); sum += c; cnt += (c > 0u) ? 1u : 0u; mine = (j == x) ? c : mine; }
; __device__ __forceinline__ void xcd_barrier(const XcdBarrier& b) {
;     asm volatile("s_waitcnt vmcnt(0)" ::: "memory");
;     __syncthreads();
;     int t0_ = threadIdx.x; asm volatile("" : "+v"(t0_));
;     if (t0_ == 0) {
;         unsigned* bar = b.bar;
;         __builtin_amdgcn_s_waitcnt(0);
;         unsigned nloc = b.st[0], nx = b.st[1];
;         if (nloc == 0u) { xcd_barrier_complete(bar, b.x, nloc, nx); b.st[0] = nloc; b.st[1] = nx; }
;         const unsigned old = xb_add(&bar[XB_XSUB(b.x)], 1u);
.LBB0_1422:
	s_mov_b64 s[40:41], s[72:73]
	s_getreg_b32 s2, hwreg(HW_REG_XCC_ID, 0, 4)
	s_waitcnt vmcnt(0)
	v_mov_b32_e32 v0, v154
	s_barrier
	s_nop 0
	v_cmp_eq_u32_e32 vcc, 0, v0
	s_and_saveexec_b64 s[38:39], vcc
	s_cbranch_execz .LBB0_1466
	s_add_i32 s3, 0, 0x21000
	v_mov_b32_e32 v0, s3
	s_waitcnt vmcnt(0) expcnt(0) lgkmcnt(0)
	buffer_wbl2 sc1
	ds_read_b32 v2, v0
	s_add_i32 s3, 0, 0x21004
	v_mov_b32_e32 v0, s3
	ds_read_b32 v0, v0
	s_and_b32 s15, s2, 15
	s_waitcnt lgkmcnt(1)
	v_cmp_ne_u32_e32 vcc, 0, v2
	s_cbranch_vccnz .LBB0_1437
	s_add_u32 s2, s40, 0x100200
	s_addc_u32 s3, s41, 0
	s_add_u32 s8, s40, 0x100400
	s_addc_u32 s9, s41, 0
	s_add_u32 s10, s40, 0x100500
	s_addc_u32 s11, s41, 0
	s_add_u32 s12, s40, 0x100600
	s_addc_u32 s13, s41, 0
	s_add_u32 s16, s40, 0x100700
	s_addc_u32 s17, s41, 0
	s_add_u32 s18, s40, 0x100800
	s_addc_u32 s19, s41, 0
	s_add_u32 s20, s40, 0x100900
	s_addc_u32 s21, s41, 0
	s_add_u32 s22, s40, 0x100a00
	s_addc_u32 s23, s41, 0
	s_add_u32 s24, s40, 0x100b00
	s_addc_u32 s25, s41, 0
	s_add_u32 s28, s40, 0x100c00
	s_addc_u32 s29, s41, 0
	s_add_u32 s30, s40, 0x100d00
	s_addc_u32 s31, s41, 0
	s_add_u32 s34, s40, 0x100e00
	s_addc_u32 s35, s41, 0
	s_add_u32 s36, s40, 0x100f00
	s_addc_u32 s37, s41, 0
	s_add_u32 s44, s40, 0x101000
	s_addc_u32 s45, s41, 0
	s_add_u32 s46, s40, 0x101100
	s_addc_u32 s47, s41, 0
	s_add_u32 s48, s40, 0x101200
	s_addc_u32 s49, s41, 0
	s_add_u32 s50, s40, 0x101300
	s_mul_i32 s26, s75, s81
	s_addc_u32 s51, s41, 0
	s_mul_i32 s26, s26, s74
	s_mov_b32 s27, 1
	s_mov_b64 s[4:5], 0
	s_waitcnt lgkmcnt(0)
	v_mov_b64_e32 v[0:1], s[8:9]
	v_mov_b64_e32 v[2:3], s[10:11]
	v_mov_b64_e32 v[4:5], s[12:13]
	v_mov_b64_e32 v[6:7], s[16:17]
	v_mov_b64_e32 v[8:9], s[18:19]
	v_mov_b64_e32 v[10:11], s[20:21]
	v_mov_b64_e32 v[12:13], s[22:23]
	v_mov_b64_e32 v[14:15], s[24:25]
	v_mov_b64_e32 v[16:17], s[28:29]
	v_mov_b64_e32 v[18:19], s[30:31]
	v_mov_b64_e32 v[20:21], s[34:35]
	v_mov_b64_e32 v[22:23], s[36:37]
	v_mov_b64_e32 v[24:25], s[44:45]
	v_mov_b64_e32 v[26:27], s[46:47]
	v_mov_b64_e32 v[28:29], s[48:49]
	v_mov_b64_e32 v[30:31], s[50:51]
	s_branch .LBB0_1427

; __device__ __forceinline__ unsigned xb_ld(unsigned* p)              { return __hip_atomic_load(p, __ATOMIC_RELAXED, __HIP_MEMORY_SCOPE_AGENT); }
; __device__ __forceinline__ unsigned xb_add(unsigned* p, unsigned v) { return __hip_atomic_fetch_add(p, v, __ATOMIC_RELAXED, __HIP_MEMORY_SCOPE_AGENT); }
; __device__ __forceinline__ void xcd_barrier_complete(unsigned* bar, unsigned x, unsigned& nloc, unsigned& nx) {
;     const unsigned G = gridDim.x * gridDim.y * gridDim.z;
;     unsigned sum, cnt, mine, sp = 0u;
;     for (;;) {
;         sum = 0u; cnt = 0u; mine = 0u;
; #pragma unroll
;         for (unsigned j = 0; j < 16; ++j) { const unsigned c = xb_ld(&bar[XB_XCNT(j)]); sum += c; cnt += (c > 0u) ? 1u : 0u; mine = (j == x) ? c : mine; }
; __device__ __forceinline__ void xcd_barrier(const XcdBarrier& b) {
;     asm volatile("s_waitcnt vmcnt(0)" ::: "memory");
;     __syncthreads();
;     int t0_ = threadIdx.x; asm volatile("" : "+v"(t0_));
;     if (t0_ == 0) {
;         unsigned* bar = b.bar;
;         __builtin_amdgcn_s_waitcnt(0);
;         unsigned nloc = b.st[0], nx = b.st[1];
;         if (nloc == 0u) { xcd_barrier_complete(bar, b.x, nloc, nx); b.st[0] = nloc; b.st[1] = nx; }
;         const unsigned old = xb_add(&bar[XB_XSUB(b.x)], 1u);
.LBB0_1486:
	s_getreg_b32 s0, hwreg(HW_REG_XCC_ID, 0, 4)
	s_waitcnt vmcnt(0)
	s_barrier
	s_nop 0
	v_cmp_eq_u32_e32 vcc, 0, v154
	s_and_saveexec_b64 s[34:35], vcc
	s_cbranch_execz .LBB0_1530
	s_add_i32 s1, 0, 0x21000
	v_mov_b32_e32 v0, s1
	s_waitcnt vmcnt(0) expcnt(0) lgkmcnt(0)
	buffer_wbl2 sc1
	ds_read_b32 v2, v0
	s_add_i32 s1, 0, 0x21004
	v_mov_b32_e32 v0, s1
	ds_read_b32 v0, v0
	s_and_b32 s33, s0, 15
	s_waitcnt lgkmcnt(1)
	v_cmp_ne_u32_e32 vcc, 0, v2
	s_cbranch_vccnz .LBB0_1501
	s_add_u32 s0, s72, 0x100200
	s_addc_u32 s1, s73, 0
	s_add_u32 s4, s72, 0x100400
	s_addc_u32 s5, s73, 0
	s_add_u32 s8, s72, 0x100500
	s_addc_u32 s9, s73, 0
	s_add_u32 s10, s72, 0x100600
	s_addc_u32 s11, s73, 0
	s_add_u32 s12, s72, 0x100700
	s_addc_u32 s13, s73, 0
	s_add_u32 s14, s72, 0x100800
	s_addc_u32 s15, s73, 0
	s_add_u32 s16, s72, 0x100900
	s_addc_u32 s17, s73, 0
	s_add_u32 s18, s72, 0x100a00
	s_addc_u32 s19, s73, 0
	s_add_u32 s20, s72, 0x100b00
	s_addc_u32 s21, s73, 0
	s_add_u32 s24, s72, 0x100c00
	s_addc_u32 s25, s73, 0
	s_add_u32 s26, s72, 0x100d00
	s_addc_u32 s27, s73, 0
	s_add_u32 s28, s72, 0x100e00
	s_addc_u32 s29, s73, 0
	s_add_u32 s30, s72, 0x100f00
	s_addc_u32 s31, s73, 0
	s_add_u32 s36, s72, 0x101000
	s_addc_u32 s37, s73, 0
	s_add_u32 s38, s72, 0x101100
	s_addc_u32 s39, s73, 0
	s_add_u32 s40, s72, 0x101200
	s_addc_u32 s41, s73, 0
	s_add_u32 s44, s72, 0x101300
	s_mul_i32 s22, s75, s81
	s_addc_u32 s45, s73, 0
	s_mul_i32 s22, s22, s74
	s_mov_b32 s23, 1
	s_mov_b64 s[2:3], 0
	s_waitcnt lgkmcnt(0)
	v_mov_b64_e32 v[0:1], s[4:5]
	v_mov_b64_e32 v[2:3], s[8:9]
	v_mov_b64_e32 v[4:5], s[10:11]
	v_mov_b64_e32 v[6:7], s[12:13]
	v_mov_b64_e32 v[8:9], s[14:15]
	v_mov_b64_e32 v[10:11], s[16:17]
	v_mov_b64_e32 v[12:13], s[18:19]
	v_mov_b64_e32 v[14:15], s[20:21]
	v_mov_b64_e32 v[16:17], s[24:25]
	v_mov_b64_e32 v[18:19], s[26:27]
	v_mov_b64_e32 v[20:21], s[28:29]
	v_mov_b64_e32 v[22:23], s[30:31]
	v_mov_b64_e32 v[24:25], s[36:37]
	v_mov_b64_e32 v[26:27], s[38:39]
	v_mov_b64_e32 v[28:29], s[40:41]
	v_mov_b64_e32 v[30:31], s[44:45]
	s_branch .LBB0_1491
